# same as previous but 16 K-rotation phases instead of 4 (tuning the L2 channel spreading)
# baseline (speedup 1.0000x reference)
.LBB0_187:
	s_lshl_b32 s28, s67, 7
	s_ashr_i32 s29, s28, 31
	s_lshl_b64 s[26:27], s[28:29], 10
	s_lshl_b64 s[6:7], s[28:29], 11
	s_add_u32 s6, s23, s6
	s_addc_u32 s7, s33, s7
	s_ashr_i32 s25, s24, 31
	s_lshl_b64 s[8:9], s[24:25], 18
	s_add_u32 s8, s56, s8
	s_addc_u32 s9, s57, s9
	v_and_b32_e32 v200, 15, v0
	v_bfe_u32 v201, v0, 4, 2
	v_and_b32_e32 v161, 7, v200
	v_xor_b32_e32 v201, v201, v161
	v_lshlrev_b32_e32 v201, 4, v201
	v_lshl_or_b32 v201, v200, 7, v201
	v_bfe_u32 v200, v0, 7, 1
	v_lshl_or_b32 v130, v200, 13, v201
	v_bfe_u32 v200, v0, 6, 1
	v_lshl_or_b32 v194, v200, 13, v201
	v_or_b32_e32 v194, 0x4000, v194
	v_xor_b32_e32 v161, 64, v130
	v_xor_b32_e32 v195, 64, v194
	v_bfe_u32 v200, v0, 3, 3
	v_and_b32_e32 v201, 7, v0
	v_xor_b32_e32 v201, v201, v200
	v_lshlrev_b32_e32 v201, 4, v201
	v_lshl_or_b32 v201, v200, 11, v201
	v_lshrrev_b32_e32 v200, 6, v0
	v_and_b32_e32 v200, 3, v200
	v_lshl_or_b32 v196, v200, 16, v201
	v_add_u32_e32 v197, 0x3c00, v196
	v_add_u32_e32 v198, 0x7800, v196
	v_add_u32_e32 v199, 0xb400, v196
	v_lshlrev_b32_e32 v200, 12, v200
	s_nop 0
	v_readfirstlane_b32 s14, v200
	s_add_u32 s14, s14, 32
	v_mov_b32_e32 v94, 0
	v_mov_b32_e32 v95, 0
	v_mov_b32_e32 v96, 0
	v_mov_b32_e32 v97, 0
	v_mov_b32_e32 v90, 0
	v_mov_b32_e32 v91, 0
	v_mov_b32_e32 v92, 0
	v_mov_b32_e32 v93, 0
	v_mov_b32_e32 v86, 0
	v_mov_b32_e32 v87, 0
	v_mov_b32_e32 v88, 0
	v_mov_b32_e32 v89, 0
	v_mov_b32_e32 v82, 0
	v_mov_b32_e32 v83, 0
	v_mov_b32_e32 v84, 0
	v_mov_b32_e32 v85, 0
	v_mov_b32_e32 v74, 0
	v_mov_b32_e32 v75, 0
	v_mov_b32_e32 v76, 0
	v_mov_b32_e32 v77, 0
	v_mov_b32_e32 v70, 0
	v_mov_b32_e32 v71, 0
	v_mov_b32_e32 v72, 0
	v_mov_b32_e32 v73, 0
	v_mov_b32_e32 v66, 0
	v_mov_b32_e32 v67, 0
	v_mov_b32_e32 v68, 0
	v_mov_b32_e32 v69, 0
	v_mov_b32_e32 v62, 0
	v_mov_b32_e32 v63, 0
	v_mov_b32_e32 v64, 0
	v_mov_b32_e32 v65, 0
	v_mov_b32_e32 v54, 0
	v_mov_b32_e32 v55, 0
	v_mov_b32_e32 v56, 0
	v_mov_b32_e32 v57, 0
	v_mov_b32_e32 v34, 0
	v_mov_b32_e32 v35, 0
	v_mov_b32_e32 v36, 0
	v_mov_b32_e32 v37, 0
	v_mov_b32_e32 v18, 0
	v_mov_b32_e32 v19, 0
	v_mov_b32_e32 v20, 0
	v_mov_b32_e32 v21, 0
	v_mov_b32_e32 v14, 0
	v_mov_b32_e32 v15, 0
	v_mov_b32_e32 v16, 0
	v_mov_b32_e32 v17, 0
	v_mov_b32_e32 v10, 0
	v_mov_b32_e32 v11, 0
	v_mov_b32_e32 v12, 0
	v_mov_b32_e32 v13, 0
	v_mov_b32_e32 v6, 0
	v_mov_b32_e32 v7, 0
	v_mov_b32_e32 v8, 0
	v_mov_b32_e32 v9, 0
	v_mov_b32_e32 v2, 0
	v_mov_b32_e32 v3, 0
	v_mov_b32_e32 v4, 0
	v_mov_b32_e32 v5, 0
	v_mov_b32_e32 v78, 0
	v_mov_b32_e32 v79, 0
	v_mov_b32_e32 v80, 0
	v_mov_b32_e32 v81, 0
	v_mov_b32_e32 v98, 0
	v_mov_b32_e32 v99, 0
	v_mov_b32_e32 v100, 0
	v_mov_b32_e32 v101, 0
	v_mov_b32_e32 v102, 0
	v_mov_b32_e32 v103, 0
	v_mov_b32_e32 v104, 0
	v_mov_b32_e32 v105, 0
	v_mov_b32_e32 v106, 0
	v_mov_b32_e32 v107, 0
	v_mov_b32_e32 v108, 0
	v_mov_b32_e32 v109, 0
	v_mov_b32_e32 v110, 0
	v_mov_b32_e32 v111, 0
	v_mov_b32_e32 v112, 0
	v_mov_b32_e32 v113, 0
	v_mov_b32_e32 v114, 0
	v_mov_b32_e32 v115, 0
	v_mov_b32_e32 v116, 0
	v_mov_b32_e32 v117, 0
	v_mov_b32_e32 v118, 0
	v_mov_b32_e32 v119, 0
	v_mov_b32_e32 v120, 0
	v_mov_b32_e32 v121, 0
	v_mov_b32_e32 v122, 0
	v_mov_b32_e32 v123, 0
	v_mov_b32_e32 v124, 0
	v_mov_b32_e32 v125, 0
	v_mov_b32_e32 v126, 0
	v_mov_b32_e32 v127, 0
	v_mov_b32_e32 v128, 0
	v_mov_b32_e32 v129, 0
	s_waitcnt lgkmcnt(0)
	s_barrier
	v_readlane_b32 s98, v255, 16
	s_lshr_b32 s98, s98, 3
	s_and_b32 s98, s98, 15
	s_lshl_b32 s98, s98, 0
	s_lshl_b32 s99, s98, 7
	s_add_u32 s6, s6, s99
	s_addc_u32 s7, s7, 0
	s_add_u32 s8, s8, s99
	s_addc_u32 s9, s9, 0
	s_add_u32 m0, s14, 0
	s_nop 0
	global_load_lds_dwordx4 v196, s[6:7] offset:0
	global_load_lds_dwordx4 v197, s[6:7] offset:1024
	global_load_lds_dwordx4 v198, s[6:7] offset:2048
	global_load_lds_dwordx4 v199, s[6:7] offset:3072
	s_add_u32 m0, s14, 16384
	s_nop 0
	global_load_lds_dwordx4 v196, s[8:9] offset:0
	global_load_lds_dwordx4 v197, s[8:9] offset:1024
	global_load_lds_dwordx4 v198, s[8:9] offset:2048
	global_load_lds_dwordx4 v199, s[8:9] offset:3072
	s_add_u32 s98, s98, 1
	s_and_b32 s98, s98, 15
	s_cmp_eq_u32 s98, 0
	s_cselect_b32 s99, 0x800, 0
	s_add_u32 s6, s6, 0x80
	s_addc_u32 s7, s7, 0
	s_sub_u32 s6, s6, s99
	s_subb_u32 s7, s7, 0
	s_add_u32 s8, s8, 0x80
	s_addc_u32 s9, s9, 0
	s_sub_u32 s8, s8, s99
	s_subb_u32 s9, s9, 0
	s_mov_b32 s25, 0
	s_waitcnt vmcnt(0)

.LBB0_552:
	s_and_b32 s34, s33, 0xff
	s_mul_i32 s4, s34, 0xab
	s_lshr_b32 s47, s4, 11
	s_mul_i32 s4, s47, 12
	s_sub_i32 s4, s33, s4
	s_and_b32 s4, s4, 0xff
	s_lshl_b32 s4, s4, 10
	s_or_b32 s48, s4, s15
	s_lshl_b32 s35, s48, 10
	s_lshl_b32 s4, s48, 11
	s_add_u32 s10, s16, s4
	s_addc_u32 s11, s17, 0
	s_lshl_b32 s46, s47, 17
	s_lshl_b32 s4, s47, 18
	s_add_u32 s12, s18, s4
	s_addc_u32 s13, s19, 0
	v_and_b32_e32 v164, 15, v0
	v_bfe_u32 v165, v0, 4, 2
	v_and_b32_e32 v111, 7, v164
	v_xor_b32_e32 v165, v165, v111
	v_lshlrev_b32_e32 v165, 4, v165
	v_lshl_or_b32 v165, v164, 7, v165
	v_bfe_u32 v164, v0, 7, 1
	v_lshl_or_b32 v100, v164, 13, v165
	v_bfe_u32 v164, v0, 6, 1
	v_lshl_or_b32 v158, v164, 13, v165
	v_or_b32_e32 v158, 0x4000, v158
	v_xor_b32_e32 v111, 64, v100
	v_xor_b32_e32 v159, 64, v158
	v_bfe_u32 v164, v0, 3, 3
	v_and_b32_e32 v165, 7, v0
	v_xor_b32_e32 v165, v165, v164
	v_lshlrev_b32_e32 v165, 4, v165
	v_lshl_or_b32 v165, v164, 11, v165
	v_lshrrev_b32_e32 v164, 6, v0
	v_and_b32_e32 v164, 3, v164
	v_lshl_or_b32 v160, v164, 16, v165
	v_add_u32_e32 v161, 0x3c00, v160
	v_add_u32_e32 v162, 0x7800, v160
	v_add_u32_e32 v163, 0xb400, v160
	v_lshlrev_b32_e32 v164, 12, v164
	s_nop 0
	v_readfirstlane_b32 s50, v164
	s_add_u32 s50, s50, 32
	v_mov_b32_e32 v94, 0
	v_mov_b32_e32 v95, 0
	v_mov_b32_e32 v96, 0
	v_mov_b32_e32 v97, 0
	v_mov_b32_e32 v90, 0
	v_mov_b32_e32 v91, 0
	v_mov_b32_e32 v92, 0
	v_mov_b32_e32 v93, 0
	v_mov_b32_e32 v82, 0
	v_mov_b32_e32 v83, 0
	v_mov_b32_e32 v84, 0
	v_mov_b32_e32 v85, 0
	v_mov_b32_e32 v78, 0
	v_mov_b32_e32 v79, 0
	v_mov_b32_e32 v80, 0
	v_mov_b32_e32 v81, 0
	v_mov_b32_e32 v74, 0
	v_mov_b32_e32 v75, 0
	v_mov_b32_e32 v76, 0
	v_mov_b32_e32 v77, 0
	v_mov_b32_e32 v70, 0
	v_mov_b32_e32 v71, 0
	v_mov_b32_e32 v72, 0
	v_mov_b32_e32 v73, 0
	v_mov_b32_e32 v66, 0
	v_mov_b32_e32 v67, 0
	v_mov_b32_e32 v68, 0
	v_mov_b32_e32 v69, 0
	v_mov_b32_e32 v58, 0
	v_mov_b32_e32 v59, 0
	v_mov_b32_e32 v60, 0
	v_mov_b32_e32 v61, 0
	v_mov_b32_e32 v26, 0
	v_mov_b32_e32 v27, 0
	v_mov_b32_e32 v28, 0
	v_mov_b32_e32 v29, 0
	v_mov_b32_e32 v22, 0
	v_mov_b32_e32 v23, 0
	v_mov_b32_e32 v24, 0
	v_mov_b32_e32 v25, 0
	v_mov_b32_e32 v18, 0
	v_mov_b32_e32 v19, 0
	v_mov_b32_e32 v20, 0
	v_mov_b32_e32 v21, 0
	v_mov_b32_e32 v14, 0
	v_mov_b32_e32 v15, 0
	v_mov_b32_e32 v16, 0
	v_mov_b32_e32 v17, 0
	v_mov_b32_e32 v10, 0
	v_mov_b32_e32 v11, 0
	v_mov_b32_e32 v12, 0
	v_mov_b32_e32 v13, 0
	v_mov_b32_e32 v6, 0
	v_mov_b32_e32 v7, 0
	v_mov_b32_e32 v8, 0
	v_mov_b32_e32 v9, 0
	v_mov_b32_e32 v2, 0
	v_mov_b32_e32 v3, 0
	v_mov_b32_e32 v4, 0
	v_mov_b32_e32 v5, 0
	v_mov_b32_e32 v86, 0
	v_mov_b32_e32 v87, 0
	v_mov_b32_e32 v88, 0
	v_mov_b32_e32 v89, 0
	v_mov_b32_e32 v114, 0
	v_mov_b32_e32 v115, 0
	v_mov_b32_e32 v116, 0
	v_mov_b32_e32 v117, 0
	v_mov_b32_e32 v118, 0
	v_mov_b32_e32 v119, 0
	v_mov_b32_e32 v120, 0
	v_mov_b32_e32 v121, 0
	v_mov_b32_e32 v122, 0
	v_mov_b32_e32 v123, 0
	v_mov_b32_e32 v124, 0
	v_mov_b32_e32 v125, 0
	v_mov_b32_e32 v138, 0
	v_mov_b32_e32 v139, 0
	v_mov_b32_e32 v140, 0
	v_mov_b32_e32 v141, 0
	v_mov_b32_e32 v142, 0
	v_mov_b32_e32 v143, 0
	v_mov_b32_e32 v144, 0
	v_mov_b32_e32 v145, 0
	v_mov_b32_e32 v146, 0
	v_mov_b32_e32 v147, 0
	v_mov_b32_e32 v148, 0
	v_mov_b32_e32 v149, 0
	v_mov_b32_e32 v150, 0
	v_mov_b32_e32 v151, 0
	v_mov_b32_e32 v152, 0
	v_mov_b32_e32 v153, 0
	v_mov_b32_e32 v154, 0
	v_mov_b32_e32 v155, 0
	v_mov_b32_e32 v156, 0
	v_mov_b32_e32 v157, 0
	s_waitcnt lgkmcnt(0)
	s_barrier
	v_readlane_b32 s98, v255, 16
	s_lshr_b32 s98, s98, 3
	s_and_b32 s98, s98, 15
	s_lshl_b32 s98, s98, 0
	s_lshl_b32 s99, s98, 7
	s_add_u32 s10, s10, s99
	s_addc_u32 s11, s11, 0
	s_add_u32 s12, s12, s99
	s_addc_u32 s13, s13, 0
	s_add_u32 m0, s50, 0
	s_nop 0
	global_load_lds_dwordx4 v160, s[10:11] offset:0
	global_load_lds_dwordx4 v161, s[10:11] offset:1024
	global_load_lds_dwordx4 v162, s[10:11] offset:2048
	global_load_lds_dwordx4 v163, s[10:11] offset:3072
	s_add_u32 m0, s50, 16384
	s_nop 0
	global_load_lds_dwordx4 v160, s[12:13] offset:0
	global_load_lds_dwordx4 v161, s[12:13] offset:1024
	global_load_lds_dwordx4 v162, s[12:13] offset:2048
	global_load_lds_dwordx4 v163, s[12:13] offset:3072
	s_add_u32 s98, s98, 1
	s_and_b32 s98, s98, 15
	s_cmp_eq_u32 s98, 0
	s_cselect_b32 s99, 0x800, 0
	s_add_u32 s10, s10, 0x80
	s_addc_u32 s11, s11, 0
	s_sub_u32 s10, s10, s99
	s_subb_u32 s11, s11, 0
	s_add_u32 s12, s12, 0x80
	s_addc_u32 s13, s13, 0
	s_sub_u32 s12, s12, s99
	s_subb_u32 s13, s13, 0
	s_mov_b32 s49, 0
	s_waitcnt vmcnt(0)

.LBB0_560:
	s_or_b64 exec, exec, s[10:11]
	s_lshl_b32 s10, s47, 7
	s_lshl_b32 s4, s35, 1
	s_add_u32 s12, s21, s4
	s_addc_u32 s13, s22, 0
	s_lshl_b32 s4, s46, 1
	v_mov_b32_e32 v111, v101
	s_add_u32 s46, s23, s4
	s_addc_u32 s47, s24, 0
	s_waitcnt lgkmcnt(0)
	s_barrier
	ds_read2_b32 v[26:27], v129 offset1:16
	ds_read2_b32 v[148:149], v129 offset0:132 offset1:148
	ds_read2_b32 v[28:29], v138 offset0:8 offset1:24
	ds_read2_b32 v[150:151], v138 offset0:140 offset1:156
	ds_read2_b32 v[22:23], v129 offset0:32 offset1:48
	ds_read2_b32 v[152:153], v129 offset0:164 offset1:180
	ds_read2_b32 v[24:25], v138 offset0:40 offset1:56
	ds_read2_b32 v[154:155], v138 offset0:172 offset1:188
	ds_read2_b32 v[18:19], v139 offset0:64 offset1:80
	ds_read2_b32 v[156:157], v139 offset0:196 offset1:212
	ds_read2_b32 v[20:21], v140 offset0:72 offset1:88
	ds_read2_b32 v[158:159], v140 offset0:204 offset1:220
	ds_read2_b32 v[14:15], v139 offset0:96 offset1:112
	ds_read2_b32 v[160:161], v139 offset0:228 offset1:244
	ds_read2_b32 v[16:17], v140 offset0:104 offset1:120
	ds_read2_b32 v[162:163], v140 offset0:236 offset1:252
	ds_read2_b32 v[10:11], v141 offset0:128 offset1:144
	ds_read2_b32 v[164:165], v142 offset0:4 offset1:20
	ds_read2_b32 v[12:13], v142 offset0:136 offset1:152
	ds_read2_b32 v[166:167], v143 offset0:12 offset1:28
	ds_read2_b32 v[6:7], v141 offset0:160 offset1:176
	ds_read2_b32 v[168:169], v142 offset0:36 offset1:52
	ds_read2_b32 v[8:9], v142 offset0:168 offset1:184
	ds_read2_b32 v[170:171], v143 offset0:44 offset1:60
	ds_read2_b32 v[2:3], v144 offset0:192 offset1:208
	ds_read2_b32 v[172:173], v145 offset0:68 offset1:84
	ds_read2_b32 v[4:5], v145 offset0:200 offset1:216
	ds_read2_b32 v[174:175], v146 offset0:76 offset1:92
	ds_read2_b32 v[30:31], v144 offset0:224 offset1:240
	ds_read2_b32 v[176:177], v145 offset0:100 offset1:116
	ds_read2_b32 v[32:33], v145 offset0:232 offset1:248
	ds_read2_b32 v[180:181], v146 offset0:108 offset1:124
	s_waitcnt lgkmcnt(0)
	s_barrier
	v_mov_b32_e32 v94, v31
	v_mov_b32_e32 v95, v177
	v_mov_b32_e32 v96, v33
	v_mov_b32_e32 v97, v181
	v_mov_b32_e32 v31, v176
	v_mov_b32_e32 v33, v180
	v_mov_b32_e32 v66, v3
	v_mov_b32_e32 v67, v173
	v_mov_b32_e32 v68, v5
	v_mov_b32_e32 v69, v175
	v_mov_b32_e32 v3, v172
	v_mov_b32_e32 v5, v174
	v_mov_b32_e32 v70, v7
	v_mov_b32_e32 v71, v169
	v_mov_b32_e32 v72, v9
	v_mov_b32_e32 v73, v171
	v_mov_b32_e32 v7, v168
	v_mov_b32_e32 v9, v170
	v_mov_b32_e32 v74, v11
	v_mov_b32_e32 v75, v165
	v_mov_b32_e32 v76, v13
	v_mov_b32_e32 v77, v167
	v_mov_b32_e32 v11, v164
	v_mov_b32_e32 v13, v166
	v_mov_b32_e32 v78, v15
	v_mov_b32_e32 v79, v161
	v_mov_b32_e32 v80, v17
	v_mov_b32_e32 v81, v163
	v_mov_b32_e32 v15, v160
	v_mov_b32_e32 v17, v162
	v_mov_b32_e32 v82, v19
	v_mov_b32_e32 v83, v157
	v_mov_b32_e32 v84, v21
	v_mov_b32_e32 v85, v159
	v_mov_b32_e32 v19, v156
	v_mov_b32_e32 v21, v158
	v_mov_b32_e32 v86, v23
	v_mov_b32_e32 v87, v153
	v_mov_b32_e32 v88, v25
	v_mov_b32_e32 v89, v155
	v_mov_b32_e32 v23, v152
	v_mov_b32_e32 v25, v154
	v_mov_b32_e32 v90, v27
	v_mov_b32_e32 v91, v149
	v_mov_b32_e32 v92, v29
	v_mov_b32_e32 v93, v151
	v_mov_b32_e32 v27, v148
	v_mov_b32_e32 v29, v150
	s_waitcnt lgkmcnt(0)
	s_barrier
	v_and_b32_e32 v174, 15, v0
	v_bfe_u32 v175, v0, 4, 2
	v_and_b32_e32 v111, 7, v174
	v_xor_b32_e32 v175, v175, v111
	v_lshlrev_b32_e32 v175, 4, v175
	v_lshl_or_b32 v175, v174, 7, v175
	v_bfe_u32 v174, v0, 7, 1
	v_lshl_or_b32 v100, v174, 13, v175
	v_bfe_u32 v174, v0, 6, 1
	v_lshl_or_b32 v168, v174, 13, v175
	v_or_b32_e32 v168, 0x4000, v168
	v_xor_b32_e32 v111, 64, v100
	v_xor_b32_e32 v169, 64, v168
	v_bfe_u32 v174, v0, 3, 3
	v_and_b32_e32 v175, 7, v0
	v_xor_b32_e32 v175, v175, v174
	v_lshlrev_b32_e32 v175, 4, v175
	v_lshl_or_b32 v175, v174, 11, v175
	v_lshrrev_b32_e32 v174, 6, v0
	v_and_b32_e32 v174, 3, v174
	v_lshl_or_b32 v170, v174, 16, v175
	v_add_u32_e32 v171, 0x3c00, v170
	v_add_u32_e32 v172, 0x7800, v170
	v_add_u32_e32 v173, 0xb400, v170
	v_lshlrev_b32_e32 v174, 12, v174
	s_nop 0
	v_readfirstlane_b32 s4, v174
	s_add_u32 s4, s4, 32
	v_mov_b32_e32 v116, 0
	v_mov_b32_e32 v117, 0
	v_mov_b32_e32 v118, 0
	v_mov_b32_e32 v119, 0
	v_mov_b32_e32 v120, 0
	v_mov_b32_e32 v121, 0
	v_mov_b32_e32 v122, 0
	v_mov_b32_e32 v123, 0
	v_mov_b32_e32 v124, 0
	v_mov_b32_e32 v125, 0
	v_mov_b32_e32 v126, 0
	v_mov_b32_e32 v127, 0
	v_mov_b32_e32 v148, 0
	v_mov_b32_e32 v149, 0
	v_mov_b32_e32 v150, 0
	v_mov_b32_e32 v151, 0
	v_mov_b32_e32 v152, 0
	v_mov_b32_e32 v153, 0
	v_mov_b32_e32 v154, 0
	v_mov_b32_e32 v155, 0
	v_mov_b32_e32 v156, 0
	v_mov_b32_e32 v157, 0
	v_mov_b32_e32 v158, 0
	v_mov_b32_e32 v159, 0
	v_mov_b32_e32 v160, 0
	v_mov_b32_e32 v161, 0
	v_mov_b32_e32 v162, 0
	v_mov_b32_e32 v163, 0
	v_mov_b32_e32 v164, 0
	v_mov_b32_e32 v165, 0
	v_mov_b32_e32 v166, 0
	v_mov_b32_e32 v167, 0
	s_waitcnt lgkmcnt(0)
	s_barrier
	v_readlane_b32 s98, v255, 16
	s_lshr_b32 s98, s98, 3
	s_and_b32 s98, s98, 15
	s_lshl_b32 s98, s98, 0
	s_lshl_b32 s99, s98, 7
	s_add_u32 s12, s12, s99
	s_addc_u32 s13, s13, 0
	s_add_u32 s46, s46, s99
	s_addc_u32 s47, s47, 0
	s_add_u32 m0, s4, 0
	s_nop 0
	global_load_lds_dwordx4 v170, s[12:13] offset:0
	global_load_lds_dwordx4 v171, s[12:13] offset:1024
	global_load_lds_dwordx4 v172, s[12:13] offset:2048
	global_load_lds_dwordx4 v173, s[12:13] offset:3072
	s_add_u32 m0, s4, 16384
	s_nop 0
	global_load_lds_dwordx4 v170, s[46:47] offset:0
	global_load_lds_dwordx4 v171, s[46:47] offset:1024
	global_load_lds_dwordx4 v172, s[46:47] offset:2048
	global_load_lds_dwordx4 v173, s[46:47] offset:3072
	s_add_u32 s98, s98, 1
	s_and_b32 s98, s98, 15
	s_cmp_eq_u32 s98, 0
	s_cselect_b32 s99, 0x800, 0
	s_add_u32 s12, s12, 0x80
	s_addc_u32 s13, s13, 0
	s_sub_u32 s12, s12, s99
	s_subb_u32 s13, s13, 0
	s_add_u32 s46, s46, 0x80
	s_addc_u32 s47, s47, 0
	s_sub_u32 s46, s46, s99
	s_subb_u32 s47, s47, 0
	s_mov_b32 s11, 0
	s_waitcnt vmcnt(0)

.LBB0_634:
	s_and_b32 s31, s30, 0xff
	s_mul_i32 s4, s31, 0xab
	s_lshr_b32 s33, s4, 11
	s_mul_i32 s4, s33, 12
	s_sub_i32 s4, s30, s4
	s_and_b32 s4, s4, 0xff
	s_lshl_b32 s4, s4, 21
	s_or_b32 s4, s4, s23
	s_add_u32 s14, s18, s4
	s_addc_u32 s15, s19, 0
	s_lshl_b32 s4, s33, 18
	s_add_u32 s16, s20, s4
	s_addc_u32 s17, s21, 0
	v_and_b32_e32 v162, 15, v0
	v_bfe_u32 v163, v0, 4, 2
	v_and_b32_e32 v109, 7, v162
	v_xor_b32_e32 v163, v163, v109
	v_lshlrev_b32_e32 v163, 4, v163
	v_lshl_or_b32 v163, v162, 7, v163
	v_bfe_u32 v162, v0, 7, 1
	v_lshl_or_b32 v100, v162, 13, v163
	v_bfe_u32 v162, v0, 6, 1
	v_lshl_or_b32 v156, v162, 13, v163
	v_or_b32_e32 v156, 0x4000, v156
	v_xor_b32_e32 v109, 64, v100
	v_xor_b32_e32 v157, 64, v156
	v_bfe_u32 v162, v0, 3, 3
	v_and_b32_e32 v163, 7, v0
	v_xor_b32_e32 v163, v163, v162
	v_lshlrev_b32_e32 v163, 4, v163
	v_lshl_or_b32 v163, v162, 11, v163
	v_lshrrev_b32_e32 v162, 6, v0
	v_and_b32_e32 v162, 3, v162
	v_lshl_or_b32 v158, v162, 16, v163
	v_add_u32_e32 v159, 0x3c00, v158
	v_add_u32_e32 v160, 0x7800, v158
	v_add_u32_e32 v161, 0xb400, v158
	v_lshlrev_b32_e32 v162, 12, v162
	s_nop 0
	v_readfirstlane_b32 s35, v162
	s_add_u32 s35, s35, 32
	v_mov_b32_e32 v94, 0
	v_mov_b32_e32 v95, 0
	v_mov_b32_e32 v96, 0
	v_mov_b32_e32 v97, 0
	v_mov_b32_e32 v90, 0
	v_mov_b32_e32 v91, 0
	v_mov_b32_e32 v92, 0
	v_mov_b32_e32 v93, 0
	v_mov_b32_e32 v82, 0
	v_mov_b32_e32 v83, 0
	v_mov_b32_e32 v84, 0
	v_mov_b32_e32 v85, 0
	v_mov_b32_e32 v78, 0
	v_mov_b32_e32 v79, 0
	v_mov_b32_e32 v80, 0
	v_mov_b32_e32 v81, 0
	v_mov_b32_e32 v74, 0
	v_mov_b32_e32 v75, 0
	v_mov_b32_e32 v76, 0
	v_mov_b32_e32 v77, 0
	v_mov_b32_e32 v70, 0
	v_mov_b32_e32 v71, 0
	v_mov_b32_e32 v72, 0
	v_mov_b32_e32 v73, 0
	v_mov_b32_e32 v66, 0
	v_mov_b32_e32 v67, 0
	v_mov_b32_e32 v68, 0
	v_mov_b32_e32 v69, 0
	v_mov_b32_e32 v62, 0
	v_mov_b32_e32 v63, 0
	v_mov_b32_e32 v64, 0
	v_mov_b32_e32 v65, 0
	v_mov_b32_e32 v34, 0
	v_mov_b32_e32 v35, 0
	v_mov_b32_e32 v36, 0
	v_mov_b32_e32 v37, 0
	v_mov_b32_e32 v26, 0
	v_mov_b32_e32 v27, 0
	v_mov_b32_e32 v28, 0
	v_mov_b32_e32 v29, 0
	v_mov_b32_e32 v18, 0
	v_mov_b32_e32 v19, 0
	v_mov_b32_e32 v20, 0
	v_mov_b32_e32 v21, 0
	v_mov_b32_e32 v14, 0
	v_mov_b32_e32 v15, 0
	v_mov_b32_e32 v16, 0
	v_mov_b32_e32 v17, 0
	v_mov_b32_e32 v10, 0
	v_mov_b32_e32 v11, 0
	v_mov_b32_e32 v12, 0
	v_mov_b32_e32 v13, 0
	v_mov_b32_e32 v6, 0
	v_mov_b32_e32 v7, 0
	v_mov_b32_e32 v8, 0
	v_mov_b32_e32 v9, 0
	v_mov_b32_e32 v2, 0
	v_mov_b32_e32 v3, 0
	v_mov_b32_e32 v4, 0
	v_mov_b32_e32 v5, 0
	v_mov_b32_e32 v86, 0
	v_mov_b32_e32 v87, 0
	v_mov_b32_e32 v88, 0
	v_mov_b32_e32 v89, 0
	v_mov_b32_e32 v110, 0
	v_mov_b32_e32 v111, 0
	v_mov_b32_e32 v112, 0
	v_mov_b32_e32 v113, 0
	v_mov_b32_e32 v114, 0
	v_mov_b32_e32 v115, 0
	v_mov_b32_e32 v116, 0
	v_mov_b32_e32 v117, 0
	v_mov_b32_e32 v118, 0
	v_mov_b32_e32 v119, 0
	v_mov_b32_e32 v120, 0
	v_mov_b32_e32 v121, 0
	v_mov_b32_e32 v136, 0
	v_mov_b32_e32 v137, 0
	v_mov_b32_e32 v138, 0
	v_mov_b32_e32 v139, 0
	v_mov_b32_e32 v140, 0
	v_mov_b32_e32 v141, 0
	v_mov_b32_e32 v142, 0
	v_mov_b32_e32 v143, 0
	v_mov_b32_e32 v144, 0
	v_mov_b32_e32 v145, 0
	v_mov_b32_e32 v146, 0
	v_mov_b32_e32 v147, 0
	v_mov_b32_e32 v148, 0
	v_mov_b32_e32 v149, 0
	v_mov_b32_e32 v150, 0
	v_mov_b32_e32 v151, 0
	v_mov_b32_e32 v152, 0
	v_mov_b32_e32 v153, 0
	v_mov_b32_e32 v154, 0
	v_mov_b32_e32 v155, 0
	s_waitcnt lgkmcnt(0)
	s_barrier
	v_readlane_b32 s98, v255, 16
	s_lshr_b32 s98, s98, 3
	s_and_b32 s98, s98, 15
	s_lshl_b32 s98, s98, 0
	s_lshl_b32 s99, s98, 7
	s_add_u32 s14, s14, s99
	s_addc_u32 s15, s15, 0
	s_add_u32 s16, s16, s99
	s_addc_u32 s17, s17, 0
	s_add_u32 m0, s35, 0
	s_nop 0
	global_load_lds_dwordx4 v158, s[14:15] offset:0
	global_load_lds_dwordx4 v159, s[14:15] offset:1024
	global_load_lds_dwordx4 v160, s[14:15] offset:2048
	global_load_lds_dwordx4 v161, s[14:15] offset:3072
	s_add_u32 m0, s35, 16384
	s_nop 0
	global_load_lds_dwordx4 v158, s[16:17] offset:0
	global_load_lds_dwordx4 v159, s[16:17] offset:1024
	global_load_lds_dwordx4 v160, s[16:17] offset:2048
	global_load_lds_dwordx4 v161, s[16:17] offset:3072
	s_add_u32 s98, s98, 1
	s_and_b32 s98, s98, 15
	s_cmp_eq_u32 s98, 0
	s_cselect_b32 s99, 0x800, 0
	s_add_u32 s14, s14, 0x80
	s_addc_u32 s15, s15, 0
	s_sub_u32 s14, s14, s99
	s_subb_u32 s15, s15, 0
	s_add_u32 s16, s16, 0x80
	s_addc_u32 s17, s17, 0
	s_sub_u32 s16, s16, s99
	s_subb_u32 s17, s17, 0
	s_mov_b32 s34, 0
	s_waitcnt vmcnt(0)

.LBB0_786:
	s_lshl_b32 s10, s48, 7
	s_xor_b64 s[46:47], s[50:51], -1
	s_or_b32 s50, s31, s10
	s_mov_b32 s51, s75
	s_lshl_b64 s[50:51], s[50:51], 11
	s_add_u32 s50, s54, s50
	s_addc_u32 s51, s55, s51
	s_waitcnt lgkmcnt(0)
	s_lshl_b32 s98, s30, 11
	s_add_u32 s98, s52, s98
	s_addc_u32 s99, s53, 0
	v_and_b32_e32 v222, 15, v0
	v_bfe_u32 v223, v0, 4, 2
	v_and_b32_e32 v141, 7, v222
	v_xor_b32_e32 v223, v223, v141
	v_lshlrev_b32_e32 v223, 4, v223
	v_lshl_or_b32 v223, v222, 7, v223
	v_bfe_u32 v222, v0, 7, 1
	v_lshl_or_b32 v140, v222, 13, v223
	v_bfe_u32 v222, v0, 6, 1
	v_lshl_or_b32 v216, v222, 13, v223
	v_or_b32_e32 v216, 0x4000, v216
	v_xor_b32_e32 v141, 64, v140
	v_xor_b32_e32 v217, 64, v216
	v_bfe_u32 v222, v0, 3, 3
	v_and_b32_e32 v223, 7, v0
	v_xor_b32_e32 v223, v223, v222
	v_lshlrev_b32_e32 v223, 4, v223
	v_lshl_or_b32 v223, v222, 11, v223
	v_lshrrev_b32_e32 v222, 6, v0
	v_and_b32_e32 v222, 3, v222
	v_lshl_or_b32 v218, v222, 16, v223
	v_add_u32_e32 v219, 0x3c00, v218
	v_add_u32_e32 v220, 0x7800, v218
	v_add_u32_e32 v221, 0xb400, v218
	v_lshlrev_b32_e32 v222, 12, v222
	s_nop 0
	v_readfirstlane_b32 s101, v222
	s_add_u32 s101, s101, 32
	v_mov_b32_e32 v86, 0
	v_mov_b32_e32 v87, 0
	v_mov_b32_e32 v88, 0
	v_mov_b32_e32 v89, 0
	v_mov_b32_e32 v82, 0
	v_mov_b32_e32 v83, 0
	v_mov_b32_e32 v84, 0
	v_mov_b32_e32 v85, 0
	v_mov_b32_e32 v78, 0
	v_mov_b32_e32 v79, 0
	v_mov_b32_e32 v80, 0
	v_mov_b32_e32 v81, 0
	v_mov_b32_e32 v74, 0
	v_mov_b32_e32 v75, 0
	v_mov_b32_e32 v76, 0
	v_mov_b32_e32 v77, 0
	v_mov_b32_e32 v70, 0
	v_mov_b32_e32 v71, 0
	v_mov_b32_e32 v72, 0
	v_mov_b32_e32 v73, 0
	v_mov_b32_e32 v90, 0
	v_mov_b32_e32 v91, 0
	v_mov_b32_e32 v92, 0
	v_mov_b32_e32 v93, 0
	v_mov_b32_e32 v94, 0
	v_mov_b32_e32 v95, 0
	v_mov_b32_e32 v96, 0
	v_mov_b32_e32 v97, 0
	v_mov_b32_e32 v6, 0
	v_mov_b32_e32 v7, 0
	v_mov_b32_e32 v8, 0
	v_mov_b32_e32 v9, 0
	v_mov_b32_e32 v2, 0
	v_mov_b32_e32 v3, 0
	v_mov_b32_e32 v4, 0
	v_mov_b32_e32 v5, 0
	v_mov_b32_e32 v10, 0
	v_mov_b32_e32 v11, 0
	v_mov_b32_e32 v12, 0
	v_mov_b32_e32 v13, 0
	v_mov_b32_e32 v14, 0
	v_mov_b32_e32 v15, 0
	v_mov_b32_e32 v16, 0
	v_mov_b32_e32 v17, 0
	v_mov_b32_e32 v26, 0
	v_mov_b32_e32 v27, 0
	v_mov_b32_e32 v28, 0
	v_mov_b32_e32 v29, 0
	v_mov_b32_e32 v34, 0
	v_mov_b32_e32 v35, 0
	v_mov_b32_e32 v36, 0
	v_mov_b32_e32 v37, 0
	v_mov_b32_e32 v30, 0
	v_mov_b32_e32 v31, 0
	v_mov_b32_e32 v32, 0
	v_mov_b32_e32 v33, 0
	v_mov_b32_e32 v22, 0
	v_mov_b32_e32 v23, 0
	v_mov_b32_e32 v24, 0
	v_mov_b32_e32 v25, 0
	v_mov_b32_e32 v18, 0
	v_mov_b32_e32 v19, 0
	v_mov_b32_e32 v20, 0
	v_mov_b32_e32 v21, 0
	v_mov_b32_e32 v136, 0
	v_mov_b32_e32 v137, 0
	v_mov_b32_e32 v138, 0
	v_mov_b32_e32 v139, 0
	v_mov_b32_e32 v188, 0
	v_mov_b32_e32 v189, 0
	v_mov_b32_e32 v190, 0
	v_mov_b32_e32 v191, 0
	v_mov_b32_e32 v192, 0
	v_mov_b32_e32 v193, 0
	v_mov_b32_e32 v194, 0
	v_mov_b32_e32 v195, 0
	v_mov_b32_e32 v196, 0
	v_mov_b32_e32 v197, 0
	v_mov_b32_e32 v198, 0
	v_mov_b32_e32 v199, 0
	v_mov_b32_e32 v200, 0
	v_mov_b32_e32 v201, 0
	v_mov_b32_e32 v202, 0
	v_mov_b32_e32 v203, 0
	v_mov_b32_e32 v204, 0
	v_mov_b32_e32 v205, 0
	v_mov_b32_e32 v206, 0
	v_mov_b32_e32 v207, 0
	v_mov_b32_e32 v208, 0
	v_mov_b32_e32 v209, 0
	v_mov_b32_e32 v210, 0
	v_mov_b32_e32 v211, 0
	v_mov_b32_e32 v212, 0
	v_mov_b32_e32 v213, 0
	v_mov_b32_e32 v214, 0
	v_mov_b32_e32 v215, 0
	s_waitcnt lgkmcnt(0)
	s_barrier
	s_lshr_b32 s49, s30, 10
	s_and_b32 s49, s49, 15
	s_lshl_b32 s49, s49, 0
	s_lshl_b32 s10, s49, 7
	s_add_u32 s98, s98, s10
	s_addc_u32 s99, s99, 0
	s_add_u32 s50, s50, s10
	s_addc_u32 s51, s51, 0
	s_add_u32 m0, s101, 0
	s_nop 0
	global_load_lds_dwordx4 v218, s[98:99] offset:0
	global_load_lds_dwordx4 v219, s[98:99] offset:1024
	global_load_lds_dwordx4 v220, s[98:99] offset:2048
	global_load_lds_dwordx4 v221, s[98:99] offset:3072
	s_add_u32 m0, s101, 16384
	s_nop 0
	global_load_lds_dwordx4 v218, s[50:51] offset:0
	global_load_lds_dwordx4 v219, s[50:51] offset:1024
	global_load_lds_dwordx4 v220, s[50:51] offset:2048
	global_load_lds_dwordx4 v221, s[50:51] offset:3072
	s_add_u32 s49, s49, 1
	s_and_b32 s49, s49, 15
	s_cmp_eq_u32 s49, 0
	s_cselect_b32 s10, 0x800, 0
	s_add_u32 s98, s98, 0x80
	s_addc_u32 s99, s99, 0
	s_sub_u32 s98, s98, s10
	s_subb_u32 s99, s99, 0
	s_add_u32 s50, s50, 0x80
	s_addc_u32 s51, s51, 0
	s_sub_u32 s50, s50, s10
	s_subb_u32 s51, s51, 0
	s_mov_b32 s100, 0
	s_waitcnt vmcnt(0)

.LBB0_927:
	s_lshl_b32 s28, s66, 7
	s_ashr_i32 s29, s28, 31
	s_lshl_b64 s[26:27], s[28:29], 10
	s_lshl_b64 s[6:7], s[28:29], 11
	s_add_u32 s6, s23, s6
	s_addc_u32 s7, s33, s7
	s_ashr_i32 s25, s24, 31
	s_lshl_b64 s[8:9], s[24:25], 18
	s_add_u32 s8, s54, s8
	s_addc_u32 s9, s55, s9
	v_and_b32_e32 v200, 15, v0
	v_bfe_u32 v201, v0, 4, 2
	v_and_b32_e32 v163, 7, v200
	v_xor_b32_e32 v201, v201, v163
	v_lshlrev_b32_e32 v201, 4, v201
	v_lshl_or_b32 v201, v200, 7, v201
	v_bfe_u32 v200, v0, 7, 1
	v_lshl_or_b32 v132, v200, 13, v201
	v_bfe_u32 v200, v0, 6, 1
	v_lshl_or_b32 v194, v200, 13, v201
	v_or_b32_e32 v194, 0x4000, v194
	v_xor_b32_e32 v163, 64, v132
	v_xor_b32_e32 v195, 64, v194
	v_bfe_u32 v200, v0, 3, 3
	v_and_b32_e32 v201, 7, v0
	v_xor_b32_e32 v201, v201, v200
	v_lshlrev_b32_e32 v201, 4, v201
	v_lshl_or_b32 v201, v200, 11, v201
	v_lshrrev_b32_e32 v200, 6, v0
	v_and_b32_e32 v200, 3, v200
	v_lshl_or_b32 v196, v200, 16, v201
	v_add_u32_e32 v197, 0x3c00, v196
	v_add_u32_e32 v198, 0x7800, v196
	v_add_u32_e32 v199, 0xb400, v196
	v_lshlrev_b32_e32 v200, 12, v200
	s_nop 0
	v_readfirstlane_b32 s14, v200
	s_add_u32 s14, s14, 32
	v_mov_b32_e32 v94, 0
	v_mov_b32_e32 v95, 0
	v_mov_b32_e32 v96, 0
	v_mov_b32_e32 v97, 0
	v_mov_b32_e32 v90, 0
	v_mov_b32_e32 v91, 0
	v_mov_b32_e32 v92, 0
	v_mov_b32_e32 v93, 0
	v_mov_b32_e32 v86, 0
	v_mov_b32_e32 v87, 0
	v_mov_b32_e32 v88, 0
	v_mov_b32_e32 v89, 0
	v_mov_b32_e32 v82, 0
	v_mov_b32_e32 v83, 0
	v_mov_b32_e32 v84, 0
	v_mov_b32_e32 v85, 0
	v_mov_b32_e32 v74, 0
	v_mov_b32_e32 v75, 0
	v_mov_b32_e32 v76, 0
	v_mov_b32_e32 v77, 0
	v_mov_b32_e32 v70, 0
	v_mov_b32_e32 v71, 0
	v_mov_b32_e32 v72, 0
	v_mov_b32_e32 v73, 0
	v_mov_b32_e32 v66, 0
	v_mov_b32_e32 v67, 0
	v_mov_b32_e32 v68, 0
	v_mov_b32_e32 v69, 0
	v_mov_b32_e32 v62, 0
	v_mov_b32_e32 v63, 0
	v_mov_b32_e32 v64, 0
	v_mov_b32_e32 v65, 0
	v_mov_b32_e32 v50, 0
	v_mov_b32_e32 v51, 0
	v_mov_b32_e32 v52, 0
	v_mov_b32_e32 v53, 0
	v_mov_b32_e32 v30, 0
	v_mov_b32_e32 v31, 0
	v_mov_b32_e32 v32, 0
	v_mov_b32_e32 v33, 0
	v_mov_b32_e32 v18, 0
	v_mov_b32_e32 v19, 0
	v_mov_b32_e32 v20, 0
	v_mov_b32_e32 v21, 0
	v_mov_b32_e32 v14, 0
	v_mov_b32_e32 v15, 0
	v_mov_b32_e32 v16, 0
	v_mov_b32_e32 v17, 0
	v_mov_b32_e32 v10, 0
	v_mov_b32_e32 v11, 0
	v_mov_b32_e32 v12, 0
	v_mov_b32_e32 v13, 0
	v_mov_b32_e32 v6, 0
	v_mov_b32_e32 v7, 0
	v_mov_b32_e32 v8, 0
	v_mov_b32_e32 v9, 0
	v_mov_b32_e32 v2, 0
	v_mov_b32_e32 v3, 0
	v_mov_b32_e32 v4, 0
	v_mov_b32_e32 v5, 0
	v_mov_b32_e32 v78, 0
	v_mov_b32_e32 v79, 0
	v_mov_b32_e32 v80, 0
	v_mov_b32_e32 v81, 0
	v_mov_b32_e32 v98, 0
	v_mov_b32_e32 v99, 0
	v_mov_b32_e32 v100, 0
	v_mov_b32_e32 v101, 0
	v_mov_b32_e32 v102, 0
	v_mov_b32_e32 v103, 0
	v_mov_b32_e32 v104, 0
	v_mov_b32_e32 v105, 0
	v_mov_b32_e32 v106, 0
	v_mov_b32_e32 v107, 0
	v_mov_b32_e32 v108, 0
	v_mov_b32_e32 v109, 0
	v_mov_b32_e32 v110, 0
	v_mov_b32_e32 v111, 0
	v_mov_b32_e32 v112, 0
	v_mov_b32_e32 v113, 0
	v_mov_b32_e32 v114, 0
	v_mov_b32_e32 v115, 0
	v_mov_b32_e32 v116, 0
	v_mov_b32_e32 v117, 0
	v_mov_b32_e32 v118, 0
	v_mov_b32_e32 v119, 0
	v_mov_b32_e32 v120, 0
	v_mov_b32_e32 v121, 0
	v_mov_b32_e32 v122, 0
	v_mov_b32_e32 v123, 0
	v_mov_b32_e32 v124, 0
	v_mov_b32_e32 v125, 0
	v_mov_b32_e32 v126, 0
	v_mov_b32_e32 v127, 0
	v_mov_b32_e32 v128, 0
	v_mov_b32_e32 v129, 0
	s_waitcnt lgkmcnt(0)
	s_barrier
	v_readlane_b32 s98, v255, 16
	s_lshr_b32 s98, s98, 3
	s_and_b32 s98, s98, 15
	s_lshl_b32 s98, s98, 0
	s_lshl_b32 s99, s98, 7
	s_add_u32 s6, s6, s99
	s_addc_u32 s7, s7, 0
	s_add_u32 s8, s8, s99
	s_addc_u32 s9, s9, 0
	s_add_u32 m0, s14, 0
	s_nop 0
	global_load_lds_dwordx4 v196, s[6:7] offset:0
	global_load_lds_dwordx4 v197, s[6:7] offset:1024
	global_load_lds_dwordx4 v198, s[6:7] offset:2048
	global_load_lds_dwordx4 v199, s[6:7] offset:3072
	s_add_u32 m0, s14, 16384
	s_nop 0
	global_load_lds_dwordx4 v196, s[8:9] offset:0
	global_load_lds_dwordx4 v197, s[8:9] offset:1024
	global_load_lds_dwordx4 v198, s[8:9] offset:2048
	global_load_lds_dwordx4 v199, s[8:9] offset:3072
	s_add_u32 s98, s98, 1
	s_and_b32 s98, s98, 15
	s_cmp_eq_u32 s98, 0
	s_cselect_b32 s99, 0x800, 0
	s_add_u32 s6, s6, 0x80
	s_addc_u32 s7, s7, 0
	s_sub_u32 s6, s6, s99
	s_subb_u32 s7, s7, 0
	s_add_u32 s8, s8, 0x80
	s_addc_u32 s9, s9, 0
	s_sub_u32 s8, s8, s99
	s_subb_u32 s9, s9, 0
	s_mov_b32 s25, 0
	s_waitcnt vmcnt(0)

.LBB0_1292:
	s_and_b32 s70, s69, 0xff
	s_mul_i32 s4, s70, 0xab
	s_lshr_b32 s73, s4, 11
	s_mul_i32 s4, s73, 12
	s_sub_i32 s4, s69, s4
	s_and_b32 s4, s4, 0xff
	s_lshl_b32 s4, s4, 10
	s_or_b32 s8, s4, s52
	s_lshl_b32 s71, s8, 10
	s_lshl_b32 s4, s8, 11
	s_add_u32 s4, s53, s4
	s_addc_u32 s5, s54, 0
	s_lshl_b32 s6, s73, 17
	s_add_i32 s72, s6, 0x100000
	s_lshl_b32 s6, s72, 1
	s_add_u32 s6, s55, s6
	s_addc_u32 s7, s56, 0
	v_and_b32_e32 v164, 15, v0
	v_bfe_u32 v165, v0, 4, 2
	v_and_b32_e32 v111, 7, v164
	v_xor_b32_e32 v165, v165, v111
	v_lshlrev_b32_e32 v165, 4, v165
	v_lshl_or_b32 v165, v164, 7, v165
	v_bfe_u32 v164, v0, 7, 1
	v_lshl_or_b32 v100, v164, 13, v165
	v_bfe_u32 v164, v0, 6, 1
	v_lshl_or_b32 v158, v164, 13, v165
	v_or_b32_e32 v158, 0x4000, v158
	v_xor_b32_e32 v111, 64, v100
	v_xor_b32_e32 v159, 64, v158
	v_bfe_u32 v164, v0, 3, 3
	v_and_b32_e32 v165, 7, v0
	v_xor_b32_e32 v165, v165, v164
	v_lshlrev_b32_e32 v165, 4, v165
	v_lshl_or_b32 v165, v164, 11, v165
	v_lshrrev_b32_e32 v164, 6, v0
	v_and_b32_e32 v164, 3, v164
	v_lshl_or_b32 v160, v164, 16, v165
	v_add_u32_e32 v161, 0x3c00, v160
	v_add_u32_e32 v162, 0x7800, v160
	v_add_u32_e32 v163, 0xb400, v160
	v_lshlrev_b32_e32 v164, 12, v164
	s_nop 0
	v_readfirstlane_b32 s10, v164
	s_add_u32 s10, s10, 32
	v_mov_b32_e32 v94, 0
	v_mov_b32_e32 v95, 0
	v_mov_b32_e32 v96, 0
	v_mov_b32_e32 v97, 0
	v_mov_b32_e32 v90, 0
	v_mov_b32_e32 v91, 0
	v_mov_b32_e32 v92, 0
	v_mov_b32_e32 v93, 0
	v_mov_b32_e32 v82, 0
	v_mov_b32_e32 v83, 0
	v_mov_b32_e32 v84, 0
	v_mov_b32_e32 v85, 0
	v_mov_b32_e32 v78, 0
	v_mov_b32_e32 v79, 0
	v_mov_b32_e32 v80, 0
	v_mov_b32_e32 v81, 0
	v_mov_b32_e32 v74, 0
	v_mov_b32_e32 v75, 0
	v_mov_b32_e32 v76, 0
	v_mov_b32_e32 v77, 0
	v_mov_b32_e32 v70, 0
	v_mov_b32_e32 v71, 0
	v_mov_b32_e32 v72, 0
	v_mov_b32_e32 v73, 0
	v_mov_b32_e32 v66, 0
	v_mov_b32_e32 v67, 0
	v_mov_b32_e32 v68, 0
	v_mov_b32_e32 v69, 0
	v_mov_b32_e32 v58, 0
	v_mov_b32_e32 v59, 0
	v_mov_b32_e32 v60, 0
	v_mov_b32_e32 v61, 0
	v_mov_b32_e32 v26, 0
	v_mov_b32_e32 v27, 0
	v_mov_b32_e32 v28, 0
	v_mov_b32_e32 v29, 0
	v_mov_b32_e32 v22, 0
	v_mov_b32_e32 v23, 0
	v_mov_b32_e32 v24, 0
	v_mov_b32_e32 v25, 0
	v_mov_b32_e32 v18, 0
	v_mov_b32_e32 v19, 0
	v_mov_b32_e32 v20, 0
	v_mov_b32_e32 v21, 0
	v_mov_b32_e32 v14, 0
	v_mov_b32_e32 v15, 0
	v_mov_b32_e32 v16, 0
	v_mov_b32_e32 v17, 0
	v_mov_b32_e32 v10, 0
	v_mov_b32_e32 v11, 0
	v_mov_b32_e32 v12, 0
	v_mov_b32_e32 v13, 0
	v_mov_b32_e32 v6, 0
	v_mov_b32_e32 v7, 0
	v_mov_b32_e32 v8, 0
	v_mov_b32_e32 v9, 0
	v_mov_b32_e32 v2, 0
	v_mov_b32_e32 v3, 0
	v_mov_b32_e32 v4, 0
	v_mov_b32_e32 v5, 0
	v_mov_b32_e32 v86, 0
	v_mov_b32_e32 v87, 0
	v_mov_b32_e32 v88, 0
	v_mov_b32_e32 v89, 0
	v_mov_b32_e32 v114, 0
	v_mov_b32_e32 v115, 0
	v_mov_b32_e32 v116, 0
	v_mov_b32_e32 v117, 0
	v_mov_b32_e32 v118, 0
	v_mov_b32_e32 v119, 0
	v_mov_b32_e32 v120, 0
	v_mov_b32_e32 v121, 0
	v_mov_b32_e32 v122, 0
	v_mov_b32_e32 v123, 0
	v_mov_b32_e32 v124, 0
	v_mov_b32_e32 v125, 0
	v_mov_b32_e32 v138, 0
	v_mov_b32_e32 v139, 0
	v_mov_b32_e32 v140, 0
	v_mov_b32_e32 v141, 0
	v_mov_b32_e32 v142, 0
	v_mov_b32_e32 v143, 0
	v_mov_b32_e32 v144, 0
	v_mov_b32_e32 v145, 0
	v_mov_b32_e32 v146, 0
	v_mov_b32_e32 v147, 0
	v_mov_b32_e32 v148, 0
	v_mov_b32_e32 v149, 0
	v_mov_b32_e32 v150, 0
	v_mov_b32_e32 v151, 0
	v_mov_b32_e32 v152, 0
	v_mov_b32_e32 v153, 0
	v_mov_b32_e32 v154, 0
	v_mov_b32_e32 v155, 0
	v_mov_b32_e32 v156, 0
	v_mov_b32_e32 v157, 0
	s_waitcnt lgkmcnt(0)
	s_barrier
	v_readlane_b32 s98, v255, 16
	s_lshr_b32 s98, s98, 3
	s_and_b32 s98, s98, 15
	s_lshl_b32 s98, s98, 0
	s_lshl_b32 s99, s98, 7
	s_add_u32 s4, s4, s99
	s_addc_u32 s5, s5, 0
	s_add_u32 s6, s6, s99
	s_addc_u32 s7, s7, 0
	s_add_u32 m0, s10, 0
	s_nop 0
	global_load_lds_dwordx4 v160, s[4:5] offset:0
	global_load_lds_dwordx4 v161, s[4:5] offset:1024
	global_load_lds_dwordx4 v162, s[4:5] offset:2048
	global_load_lds_dwordx4 v163, s[4:5] offset:3072
	s_add_u32 m0, s10, 16384
	s_nop 0
	global_load_lds_dwordx4 v160, s[6:7] offset:0
	global_load_lds_dwordx4 v161, s[6:7] offset:1024
	global_load_lds_dwordx4 v162, s[6:7] offset:2048
	global_load_lds_dwordx4 v163, s[6:7] offset:3072
	s_add_u32 s98, s98, 1
	s_and_b32 s98, s98, 15
	s_cmp_eq_u32 s98, 0
	s_cselect_b32 s99, 0x800, 0
	s_add_u32 s4, s4, 0x80
	s_addc_u32 s5, s5, 0
	s_sub_u32 s4, s4, s99
	s_subb_u32 s5, s5, 0
	s_add_u32 s6, s6, 0x80
	s_addc_u32 s7, s7, 0
	s_sub_u32 s6, s6, s99
	s_subb_u32 s7, s7, 0
	s_mov_b32 s9, 0
	s_waitcnt vmcnt(0)

.LBB0_1300:
	s_or_b64 exec, exec, s[50:51]
	s_lshl_b32 s4, s73, 7
	s_lshl_b32 s5, s71, 1
	s_add_u32 s6, s58, s5
	s_addc_u32 s7, s59, 0
	s_lshl_b32 s5, s72, 1
	v_mov_b32_e32 v111, v101
	s_add_u32 s8, s60, s5
	s_addc_u32 s9, s61, 0
	s_waitcnt lgkmcnt(0)
	s_barrier
	ds_read2_b32 v[26:27], v129 offset1:16
	ds_read2_b32 v[148:149], v129 offset0:132 offset1:148
	ds_read2_b32 v[28:29], v138 offset0:8 offset1:24
	ds_read2_b32 v[150:151], v138 offset0:140 offset1:156
	ds_read2_b32 v[22:23], v129 offset0:32 offset1:48
	ds_read2_b32 v[152:153], v129 offset0:164 offset1:180
	ds_read2_b32 v[24:25], v138 offset0:40 offset1:56
	ds_read2_b32 v[154:155], v138 offset0:172 offset1:188
	ds_read2_b32 v[18:19], v139 offset0:64 offset1:80
	ds_read2_b32 v[156:157], v139 offset0:196 offset1:212
	ds_read2_b32 v[20:21], v140 offset0:72 offset1:88
	ds_read2_b32 v[158:159], v140 offset0:204 offset1:220
	ds_read2_b32 v[14:15], v139 offset0:96 offset1:112
	ds_read2_b32 v[160:161], v139 offset0:228 offset1:244
	ds_read2_b32 v[16:17], v140 offset0:104 offset1:120
	ds_read2_b32 v[162:163], v140 offset0:236 offset1:252
	ds_read2_b32 v[10:11], v141 offset0:128 offset1:144
	ds_read2_b32 v[164:165], v142 offset0:4 offset1:20
	ds_read2_b32 v[12:13], v142 offset0:136 offset1:152
	ds_read2_b32 v[166:167], v143 offset0:12 offset1:28
	ds_read2_b32 v[6:7], v141 offset0:160 offset1:176
	ds_read2_b32 v[168:169], v142 offset0:36 offset1:52
	ds_read2_b32 v[8:9], v142 offset0:168 offset1:184
	ds_read2_b32 v[170:171], v143 offset0:44 offset1:60
	ds_read2_b32 v[2:3], v144 offset0:192 offset1:208
	ds_read2_b32 v[172:173], v145 offset0:68 offset1:84
	ds_read2_b32 v[4:5], v145 offset0:200 offset1:216
	ds_read2_b32 v[174:175], v146 offset0:76 offset1:92
	ds_read2_b32 v[30:31], v144 offset0:224 offset1:240
	ds_read2_b32 v[176:177], v145 offset0:100 offset1:116
	ds_read2_b32 v[32:33], v145 offset0:232 offset1:248
	ds_read2_b32 v[178:179], v146 offset0:108 offset1:124
	s_waitcnt lgkmcnt(0)
	s_barrier
	v_mov_b32_e32 v94, v31
	v_mov_b32_e32 v95, v177
	v_mov_b32_e32 v96, v33
	v_mov_b32_e32 v97, v179
	v_mov_b32_e32 v31, v176
	v_mov_b32_e32 v33, v178
	v_mov_b32_e32 v66, v3
	v_mov_b32_e32 v67, v173
	v_mov_b32_e32 v68, v5
	v_mov_b32_e32 v69, v175
	v_mov_b32_e32 v3, v172
	v_mov_b32_e32 v5, v174
	v_mov_b32_e32 v70, v7
	v_mov_b32_e32 v71, v169
	v_mov_b32_e32 v72, v9
	v_mov_b32_e32 v73, v171
	v_mov_b32_e32 v7, v168
	v_mov_b32_e32 v9, v170
	v_mov_b32_e32 v74, v11
	v_mov_b32_e32 v75, v165
	v_mov_b32_e32 v76, v13
	v_mov_b32_e32 v77, v167
	v_mov_b32_e32 v11, v164
	v_mov_b32_e32 v13, v166
	v_mov_b32_e32 v78, v15
	v_mov_b32_e32 v79, v161
	v_mov_b32_e32 v80, v17
	v_mov_b32_e32 v81, v163
	v_mov_b32_e32 v15, v160
	v_mov_b32_e32 v17, v162
	v_mov_b32_e32 v82, v19
	v_mov_b32_e32 v83, v157
	v_mov_b32_e32 v84, v21
	v_mov_b32_e32 v85, v159
	v_mov_b32_e32 v19, v156
	v_mov_b32_e32 v21, v158
	v_mov_b32_e32 v86, v23
	v_mov_b32_e32 v87, v153
	v_mov_b32_e32 v88, v25
	v_mov_b32_e32 v89, v155
	v_mov_b32_e32 v23, v152
	v_mov_b32_e32 v25, v154
	v_mov_b32_e32 v90, v27
	v_mov_b32_e32 v91, v149
	v_mov_b32_e32 v92, v29
	v_mov_b32_e32 v93, v151
	v_mov_b32_e32 v27, v148
	v_mov_b32_e32 v29, v150
	s_waitcnt lgkmcnt(0)
	s_barrier
	v_and_b32_e32 v174, 15, v0
	v_bfe_u32 v175, v0, 4, 2
	v_and_b32_e32 v111, 7, v174
	v_xor_b32_e32 v175, v175, v111
	v_lshlrev_b32_e32 v175, 4, v175
	v_lshl_or_b32 v175, v174, 7, v175
	v_bfe_u32 v174, v0, 7, 1
	v_lshl_or_b32 v100, v174, 13, v175
	v_bfe_u32 v174, v0, 6, 1
	v_lshl_or_b32 v168, v174, 13, v175
	v_or_b32_e32 v168, 0x4000, v168
	v_xor_b32_e32 v111, 64, v100
	v_xor_b32_e32 v169, 64, v168
	v_bfe_u32 v174, v0, 3, 3
	v_and_b32_e32 v175, 7, v0
	v_xor_b32_e32 v175, v175, v174
	v_lshlrev_b32_e32 v175, 4, v175
	v_lshl_or_b32 v175, v174, 11, v175
	v_lshrrev_b32_e32 v174, 6, v0
	v_and_b32_e32 v174, 3, v174
	v_lshl_or_b32 v170, v174, 16, v175
	v_add_u32_e32 v171, 0x3c00, v170
	v_add_u32_e32 v172, 0x7800, v170
	v_add_u32_e32 v173, 0xb400, v170
	v_lshlrev_b32_e32 v174, 12, v174
	s_nop 0
	v_readfirstlane_b32 s36, v174
	s_add_u32 s36, s36, 32
	v_mov_b32_e32 v116, 0
	v_mov_b32_e32 v117, 0
	v_mov_b32_e32 v118, 0
	v_mov_b32_e32 v119, 0
	v_mov_b32_e32 v120, 0
	v_mov_b32_e32 v121, 0
	v_mov_b32_e32 v122, 0
	v_mov_b32_e32 v123, 0
	v_mov_b32_e32 v124, 0
	v_mov_b32_e32 v125, 0
	v_mov_b32_e32 v126, 0
	v_mov_b32_e32 v127, 0
	v_mov_b32_e32 v148, 0
	v_mov_b32_e32 v149, 0
	v_mov_b32_e32 v150, 0
	v_mov_b32_e32 v151, 0
	v_mov_b32_e32 v152, 0
	v_mov_b32_e32 v153, 0
	v_mov_b32_e32 v154, 0
	v_mov_b32_e32 v155, 0
	v_mov_b32_e32 v156, 0
	v_mov_b32_e32 v157, 0
	v_mov_b32_e32 v158, 0
	v_mov_b32_e32 v159, 0
	v_mov_b32_e32 v160, 0
	v_mov_b32_e32 v161, 0
	v_mov_b32_e32 v162, 0
	v_mov_b32_e32 v163, 0
	v_mov_b32_e32 v164, 0
	v_mov_b32_e32 v165, 0
	v_mov_b32_e32 v166, 0
	v_mov_b32_e32 v167, 0
	s_waitcnt lgkmcnt(0)
	s_barrier
	v_readlane_b32 s98, v255, 16
	s_lshr_b32 s98, s98, 3
	s_and_b32 s98, s98, 15
	s_lshl_b32 s98, s98, 0
	s_lshl_b32 s99, s98, 7
	s_add_u32 s6, s6, s99
	s_addc_u32 s7, s7, 0
	s_add_u32 s8, s8, s99
	s_addc_u32 s9, s9, 0
	s_add_u32 m0, s36, 0
	s_nop 0
	global_load_lds_dwordx4 v170, s[6:7] offset:0
	global_load_lds_dwordx4 v171, s[6:7] offset:1024
	global_load_lds_dwordx4 v172, s[6:7] offset:2048
	global_load_lds_dwordx4 v173, s[6:7] offset:3072
	s_add_u32 m0, s36, 16384
	s_nop 0
	global_load_lds_dwordx4 v170, s[8:9] offset:0
	global_load_lds_dwordx4 v171, s[8:9] offset:1024
	global_load_lds_dwordx4 v172, s[8:9] offset:2048
	global_load_lds_dwordx4 v173, s[8:9] offset:3072
	s_add_u32 s98, s98, 1
	s_and_b32 s98, s98, 15
	s_cmp_eq_u32 s98, 0
	s_cselect_b32 s99, 0x800, 0
	s_add_u32 s6, s6, 0x80
	s_addc_u32 s7, s7, 0
	s_sub_u32 s6, s6, s99
	s_subb_u32 s7, s7, 0
	s_add_u32 s8, s8, 0x80
	s_addc_u32 s9, s9, 0
	s_sub_u32 s8, s8, s99
	s_subb_u32 s9, s9, 0
	s_mov_b32 s5, 0
	s_waitcnt vmcnt(0)

.LBB0_1372:
	s_and_b32 s28, s11, 0xff
	s_mul_i32 s2, s28, 0xab
	s_lshr_b32 s29, s2, 11
	s_mul_i32 s2, s29, 12
	s_sub_i32 s2, s11, s2
	s_and_b32 s2, s2, 0xff
	s_lshl_b32 s2, s2, 21
	s_or_b32 s2, s2, s21
	s_add_u32 s14, s16, s2
	s_addc_u32 s15, s17, 0
	s_lshl_b32 s2, s29, 18
	s_add_u32 s12, s18, s2
	s_addc_u32 s13, s19, 0
	v_and_b32_e32 v162, 15, v0
	v_bfe_u32 v163, v0, 4, 2
	v_and_b32_e32 v107, 7, v162
	v_xor_b32_e32 v163, v163, v107
	v_lshlrev_b32_e32 v163, 4, v163
	v_lshl_or_b32 v163, v162, 7, v163
	v_bfe_u32 v162, v0, 7, 1
	v_lshl_or_b32 v98, v162, 13, v163
	v_bfe_u32 v162, v0, 6, 1
	v_lshl_or_b32 v156, v162, 13, v163
	v_or_b32_e32 v156, 0x4000, v156
	v_xor_b32_e32 v107, 64, v98
	v_xor_b32_e32 v157, 64, v156
	v_bfe_u32 v162, v0, 3, 3
	v_and_b32_e32 v163, 7, v0
	v_xor_b32_e32 v163, v163, v162
	v_lshlrev_b32_e32 v163, 4, v163
	v_lshl_or_b32 v163, v162, 11, v163
	v_lshrrev_b32_e32 v162, 6, v0
	v_and_b32_e32 v162, 3, v162
	v_lshl_or_b32 v158, v162, 16, v163
	v_add_u32_e32 v159, 0x3c00, v158
	v_add_u32_e32 v160, 0x7800, v158
	v_add_u32_e32 v161, 0xb400, v158
	v_lshlrev_b32_e32 v162, 12, v162
	s_nop 0
	v_readfirstlane_b32 s31, v162
	s_add_u32 s31, s31, 32
	v_mov_b32_e32 v94, 0
	v_mov_b32_e32 v95, 0
	v_mov_b32_e32 v96, 0
	v_mov_b32_e32 v97, 0
	v_mov_b32_e32 v90, 0
	v_mov_b32_e32 v91, 0
	v_mov_b32_e32 v92, 0
	v_mov_b32_e32 v93, 0
	v_mov_b32_e32 v82, 0
	v_mov_b32_e32 v83, 0
	v_mov_b32_e32 v84, 0
	v_mov_b32_e32 v85, 0
	v_mov_b32_e32 v78, 0
	v_mov_b32_e32 v79, 0
	v_mov_b32_e32 v80, 0
	v_mov_b32_e32 v81, 0
	v_mov_b32_e32 v74, 0
	v_mov_b32_e32 v75, 0
	v_mov_b32_e32 v76, 0
	v_mov_b32_e32 v77, 0
	v_mov_b32_e32 v70, 0
	v_mov_b32_e32 v71, 0
	v_mov_b32_e32 v72, 0
	v_mov_b32_e32 v73, 0
	v_mov_b32_e32 v66, 0
	v_mov_b32_e32 v67, 0
	v_mov_b32_e32 v68, 0
	v_mov_b32_e32 v69, 0
	v_mov_b32_e32 v62, 0
	v_mov_b32_e32 v63, 0
	v_mov_b32_e32 v64, 0
	v_mov_b32_e32 v65, 0
	v_mov_b32_e32 v58, 0
	v_mov_b32_e32 v59, 0
	v_mov_b32_e32 v60, 0
	v_mov_b32_e32 v61, 0
	v_mov_b32_e32 v42, 0
	v_mov_b32_e32 v43, 0
	v_mov_b32_e32 v44, 0
	v_mov_b32_e32 v45, 0
	v_mov_b32_e32 v22, 0
	v_mov_b32_e32 v23, 0
	v_mov_b32_e32 v24, 0
	v_mov_b32_e32 v25, 0
	v_mov_b32_e32 v14, 0
	v_mov_b32_e32 v15, 0
	v_mov_b32_e32 v16, 0
	v_mov_b32_e32 v17, 0
	v_mov_b32_e32 v10, 0
	v_mov_b32_e32 v11, 0
	v_mov_b32_e32 v12, 0
	v_mov_b32_e32 v13, 0
	v_mov_b32_e32 v6, 0
	v_mov_b32_e32 v7, 0
	v_mov_b32_e32 v8, 0
	v_mov_b32_e32 v9, 0
	v_mov_b32_e32 v2, 0
	v_mov_b32_e32 v3, 0
	v_mov_b32_e32 v4, 0
	v_mov_b32_e32 v5, 0
	v_mov_b32_e32 v86, 0
	v_mov_b32_e32 v87, 0
	v_mov_b32_e32 v88, 0
	v_mov_b32_e32 v89, 0
	v_mov_b32_e32 v108, 0
	v_mov_b32_e32 v109, 0
	v_mov_b32_e32 v110, 0
	v_mov_b32_e32 v111, 0
	v_mov_b32_e32 v112, 0
	v_mov_b32_e32 v113, 0
	v_mov_b32_e32 v114, 0
	v_mov_b32_e32 v115, 0
	v_mov_b32_e32 v116, 0
	v_mov_b32_e32 v117, 0
	v_mov_b32_e32 v118, 0
	v_mov_b32_e32 v119, 0
	v_mov_b32_e32 v136, 0
	v_mov_b32_e32 v137, 0
	v_mov_b32_e32 v138, 0
	v_mov_b32_e32 v139, 0
	v_mov_b32_e32 v140, 0
	v_mov_b32_e32 v141, 0
	v_mov_b32_e32 v142, 0
	v_mov_b32_e32 v143, 0
	v_mov_b32_e32 v144, 0
	v_mov_b32_e32 v145, 0
	v_mov_b32_e32 v146, 0
	v_mov_b32_e32 v147, 0
	v_mov_b32_e32 v148, 0
	v_mov_b32_e32 v149, 0
	v_mov_b32_e32 v150, 0
	v_mov_b32_e32 v151, 0
	v_mov_b32_e32 v152, 0
	v_mov_b32_e32 v153, 0
	v_mov_b32_e32 v154, 0
	v_mov_b32_e32 v155, 0
	s_waitcnt lgkmcnt(0)
	s_barrier
	v_readlane_b32 s98, v255, 16
	s_lshr_b32 s98, s98, 3
	s_and_b32 s98, s98, 15
	s_lshl_b32 s98, s98, 0
	s_lshl_b32 s99, s98, 7
	s_add_u32 s14, s14, s99
	s_addc_u32 s15, s15, 0
	s_add_u32 s12, s12, s99
	s_addc_u32 s13, s13, 0
	s_add_u32 m0, s31, 0
	s_nop 0
	global_load_lds_dwordx4 v158, s[14:15] offset:0
	global_load_lds_dwordx4 v159, s[14:15] offset:1024
	global_load_lds_dwordx4 v160, s[14:15] offset:2048
	global_load_lds_dwordx4 v161, s[14:15] offset:3072
	s_add_u32 m0, s31, 16384
	s_nop 0
	global_load_lds_dwordx4 v158, s[12:13] offset:0
	global_load_lds_dwordx4 v159, s[12:13] offset:1024
	global_load_lds_dwordx4 v160, s[12:13] offset:2048
	global_load_lds_dwordx4 v161, s[12:13] offset:3072
	s_add_u32 s98, s98, 1
	s_and_b32 s98, s98, 15
	s_cmp_eq_u32 s98, 0
	s_cselect_b32 s99, 0x800, 0
	s_add_u32 s14, s14, 0x80
	s_addc_u32 s15, s15, 0
	s_sub_u32 s14, s14, s99
	s_subb_u32 s15, s15, 0
	s_add_u32 s12, s12, 0x80
	s_addc_u32 s13, s13, 0
	s_sub_u32 s12, s12, s99
	s_subb_u32 s13, s13, 0
	s_mov_b32 s30, 0
	s_waitcnt vmcnt(0)

.LBB0_1496:
	s_lshl_b32 s10, s50, 7
	s_or_b32 s46, s37, s10
	s_xor_b64 s[48:49], s[52:53], -1
	s_lshl_b64 s[52:53], s[46:47], 11
	s_add_u32 s52, s55, s52
	s_addc_u32 s53, s56, s53
	s_waitcnt lgkmcnt(0)
	s_lshl_b32 s98, s36, 11
	s_add_u32 s98, s33, s98
	s_addc_u32 s99, s54, 0
	v_and_b32_e32 v212, 15, v0
	v_bfe_u32 v213, v0, 4, 2
	v_and_b32_e32 v139, 7, v212
	v_xor_b32_e32 v213, v213, v139
	v_lshlrev_b32_e32 v213, 4, v213
	v_lshl_or_b32 v213, v212, 7, v213
	v_bfe_u32 v212, v0, 7, 1
	v_lshl_or_b32 v138, v212, 13, v213
	v_bfe_u32 v212, v0, 6, 1
	v_lshl_or_b32 v206, v212, 13, v213
	v_or_b32_e32 v206, 0x4000, v206
	v_xor_b32_e32 v139, 64, v138
	v_xor_b32_e32 v207, 64, v206
	v_bfe_u32 v212, v0, 3, 3
	v_and_b32_e32 v213, 7, v0
	v_xor_b32_e32 v213, v213, v212
	v_lshlrev_b32_e32 v213, 4, v213
	v_lshl_or_b32 v213, v212, 11, v213
	v_lshrrev_b32_e32 v212, 6, v0
	v_and_b32_e32 v212, 3, v212
	v_lshl_or_b32 v208, v212, 16, v213
	v_add_u32_e32 v209, 0x3c00, v208
	v_add_u32_e32 v210, 0x7800, v208
	v_add_u32_e32 v211, 0xb400, v208
	v_lshlrev_b32_e32 v212, 12, v212
	s_nop 0
	v_readfirstlane_b32 s101, v212
	s_add_u32 s101, s101, 32
	v_mov_b32_e32 v66, 0
	v_mov_b32_e32 v67, 0
	v_mov_b32_e32 v68, 0
	v_mov_b32_e32 v69, 0
	v_mov_b32_e32 v58, 0
	v_mov_b32_e32 v59, 0
	v_mov_b32_e32 v60, 0
	v_mov_b32_e32 v61, 0
	v_mov_b32_e32 v54, 0
	v_mov_b32_e32 v55, 0
	v_mov_b32_e32 v56, 0
	v_mov_b32_e32 v57, 0
	v_mov_b32_e32 v50, 0
	v_mov_b32_e32 v51, 0
	v_mov_b32_e32 v52, 0
	v_mov_b32_e32 v53, 0
	v_mov_b32_e32 v46, 0
	v_mov_b32_e32 v47, 0
	v_mov_b32_e32 v48, 0
	v_mov_b32_e32 v49, 0
	v_mov_b32_e32 v42, 0
	v_mov_b32_e32 v43, 0
	v_mov_b32_e32 v44, 0
	v_mov_b32_e32 v45, 0
	v_mov_b32_e32 v38, 0
	v_mov_b32_e32 v39, 0
	v_mov_b32_e32 v40, 0
	v_mov_b32_e32 v41, 0
	v_mov_b32_e32 v6, 0
	v_mov_b32_e32 v7, 0
	v_mov_b32_e32 v8, 0
	v_mov_b32_e32 v9, 0
	v_mov_b32_e32 v2, 0
	v_mov_b32_e32 v3, 0
	v_mov_b32_e32 v4, 0
	v_mov_b32_e32 v5, 0
	v_mov_b32_e32 v22, 0
	v_mov_b32_e32 v23, 0
	v_mov_b32_e32 v24, 0
	v_mov_b32_e32 v25, 0
	v_mov_b32_e32 v18, 0
	v_mov_b32_e32 v19, 0
	v_mov_b32_e32 v20, 0
	v_mov_b32_e32 v21, 0
	v_mov_b32_e32 v14, 0
	v_mov_b32_e32 v15, 0
	v_mov_b32_e32 v16, 0
	v_mov_b32_e32 v17, 0
	v_mov_b32_e32 v10, 0
	v_mov_b32_e32 v11, 0
	v_mov_b32_e32 v12, 0
	v_mov_b32_e32 v13, 0
	v_mov_b32_e32 v34, 0
	v_mov_b32_e32 v35, 0
	v_mov_b32_e32 v36, 0
	v_mov_b32_e32 v37, 0
	v_mov_b32_e32 v30, 0
	v_mov_b32_e32 v31, 0
	v_mov_b32_e32 v32, 0
	v_mov_b32_e32 v33, 0
	v_mov_b32_e32 v26, 0
	v_mov_b32_e32 v27, 0
	v_mov_b32_e32 v28, 0
	v_mov_b32_e32 v29, 0
	v_mov_b32_e32 v134, 0
	v_mov_b32_e32 v135, 0
	v_mov_b32_e32 v136, 0
	v_mov_b32_e32 v137, 0
	v_mov_b32_e32 v178, 0
	v_mov_b32_e32 v179, 0
	v_mov_b32_e32 v180, 0
	v_mov_b32_e32 v181, 0
	v_mov_b32_e32 v182, 0
	v_mov_b32_e32 v183, 0
	v_mov_b32_e32 v184, 0
	v_mov_b32_e32 v185, 0
	v_mov_b32_e32 v186, 0
	v_mov_b32_e32 v187, 0
	v_mov_b32_e32 v188, 0
	v_mov_b32_e32 v189, 0
	v_mov_b32_e32 v190, 0
	v_mov_b32_e32 v191, 0
	v_mov_b32_e32 v192, 0
	v_mov_b32_e32 v193, 0
	v_mov_b32_e32 v194, 0
	v_mov_b32_e32 v195, 0
	v_mov_b32_e32 v196, 0
	v_mov_b32_e32 v197, 0
	v_mov_b32_e32 v198, 0
	v_mov_b32_e32 v199, 0
	v_mov_b32_e32 v200, 0
	v_mov_b32_e32 v201, 0
	v_mov_b32_e32 v202, 0
	v_mov_b32_e32 v203, 0
	v_mov_b32_e32 v204, 0
	v_mov_b32_e32 v205, 0
	s_waitcnt lgkmcnt(0)
	s_barrier
	s_lshr_b32 s46, s36, 10
	s_and_b32 s46, s46, 15
	s_lshl_b32 s46, s46, 0
	s_lshl_b32 s51, s46, 7
	s_add_u32 s98, s98, s51
	s_addc_u32 s99, s99, 0
	s_add_u32 s52, s52, s51
	s_addc_u32 s53, s53, 0
	s_add_u32 m0, s101, 0
	s_nop 0
	global_load_lds_dwordx4 v208, s[98:99] offset:0
	global_load_lds_dwordx4 v209, s[98:99] offset:1024
	global_load_lds_dwordx4 v210, s[98:99] offset:2048
	global_load_lds_dwordx4 v211, s[98:99] offset:3072
	s_add_u32 m0, s101, 16384
	s_nop 0
	global_load_lds_dwordx4 v208, s[52:53] offset:0
	global_load_lds_dwordx4 v209, s[52:53] offset:1024
	global_load_lds_dwordx4 v210, s[52:53] offset:2048
	global_load_lds_dwordx4 v211, s[52:53] offset:3072
	s_add_u32 s46, s46, 1
	s_and_b32 s46, s46, 15
	s_cmp_eq_u32 s46, 0
	s_cselect_b32 s51, 0x800, 0
	s_add_u32 s98, s98, 0x80
	s_addc_u32 s99, s99, 0
	s_sub_u32 s98, s98, s51
	s_subb_u32 s99, s99, 0
	s_add_u32 s52, s52, 0x80
	s_addc_u32 s53, s53, 0
	s_sub_u32 s52, s52, s51
	s_subb_u32 s53, s53, 0
	s_mov_b32 s100, 0
	s_waitcnt vmcnt(0)
